# in-proj: per-CU rotated K order (first K slice = 2*(CU%8)) on the LDS-DMA loop so CUs of an XCD stream different K slices at any instant; f32 accumulation order rotated only
# speedup vs baseline: 1.0152x; 1.0079x over previous
; DI int tidx() { int t = threadIdx.x; asm volatile("" : "+v"(t)); return t; }
; template <int EPI>
; DI void gemm_phase(const P& p, int l, const u16* __restrict__ A, const u16* __restrict__ Bt, int mpx, char* lds) {
;   const int tid = tidx();
;   int t = 0;
;   int m0, n0;
;   if (!tile_coords<EPI>(t, mpx, m0, n0)) return;
;   const unsigned voffb = (unsigned)(((tid >> 3) * 1024 + (tid & 7) * 8) * 2);
;   const u16* Ag = A + (size_t)m0 * 1024;
;   const u16* Bg = Bt + (size_t)n0 * 1024;
;   uint4 ra0, ra1, ra2, ra3, rb0, rb1, rb2, rb3;
;     ...
;   GLOAD(Ag, Bg, 0)
;   u16* As0 = (u16*)lds;
;   u16* Bs0 = As0 + 256 * 64;
;   u16* As1 = Bs0 + 256 * 64;
;   u16* Bs1 = As1 + 256 * 64;
;   const int lw = (tid >> 3) * 64 + (((tid & 7) ^ ((tid >> 3) & 7)) * 8);
;   GSTORE(As0, Bs0)
.Ltile_fix_done:
	s_mul_i32 s1, s50, 0x780000
	s_mul_hi_i32 s0, s50, 0x780000
	s_add_u32 s24, s12, s1
	s_addc_u32 s25, s13, s0
	s_lshl_b32 s52, s50, 6
	s_ashr_i32 s53, s52, 31
	v_lshlrev_b32_e32 v2, 4, v0
	v_readlane_b32 s0, v254, 60
	v_ashrrev_i32_e32 v34, 3, v0
	v_and_b32_e32 v2, 0x70, v2
	s_add_u32 s0, s24, s0
	v_lshl_or_b32 v196, v34, 11, v2
	s_addc_u32 s1, s25, 0
	v_mov_b32_e32 v197, v1
	v_readlane_b32 s26, v254, 61
	v_readlane_b32 s27, v254, 62
	v_lshl_add_u64 v[30:31], s[0:1], 0, v[196:197]
	v_readlane_b32 s42, v255, 1
	global_load_dwordx4 v[18:21], v196, s[0:1]
	v_add_co_u32_e32 v22, vcc, s33, v30
	s_nop 0
	global_load_dwordx4 v[6:9], v196, s[26:27]
	v_readlane_b32 s26, v254, 63
	v_readlane_b32 s43, v255, 2
	v_readlane_b32 s27, v255, 0
	v_addc_co_u32_e32 v23, vcc, 0, v31, vcc
	v_add_co_u32_e32 v26, vcc, s35, v30
	s_nop 1
	global_load_dwordx4 v[2:5], v196, s[42:43]
	global_load_dwordx4 v[10:13], v196, s[26:27]
	v_readlane_b32 s26, v255, 3
	v_readlane_b32 s27, v255, 4
	v_addc_co_u32_e32 v27, vcc, 0, v31, vcc
	v_add_co_u32_e32 v30, vcc, s39, v30
	v_lshrrev_b32_e32 v35, 4, v0
	s_nop 1
	global_load_dwordx4 v[14:17], v196, s[26:27]
	s_nop 0
	global_load_dwordx4 v[22:25], v[22:23], off
	s_nop 0
	global_load_dwordx4 v[26:29], v[26:27], off
	v_addc_co_u32_e32 v31, vcc, 0, v31, vcc
	global_load_dwordx4 v[30:33], v[30:31], off
	v_bfe_u32 v36, v0, 4, 2
	v_and_b32_e32 v37, 7, v0
	v_lshlrev_b32_e32 v38, 7, v0
	v_lshlrev_b32_e32 v39, 6, v0
	v_xor_b32_e32 v0, v34, v0
	v_bitop3_b32 v35, v35, v37, 3 bitop3:0x6c
	v_bitop3_b32 v36, v36, v37, 4 bitop3:0x36
	v_lshlrev_b32_e32 v0, 4, v0
	s_load_dword s2, s[76:77], 0x0
	v_and_b32_e32 v37, 0x6000, v38
	v_and_b32_e32 v39, 0xffffc000, v39
	v_lshlrev_b32_e32 v35, 4, v35
	v_lshlrev_b32_e32 v36, 4, v36
	v_and_b32_e32 v0, 0x70, v0
	v_readlane_b32 s40, v255, 23
	v_and_b32_e32 v38, 0x780, v38
	v_add_u32_e32 v40, 32, v35
	v_add_u32_e32 v41, 32, v36
	v_add3_u32 v42, s40, v35, v37
	v_add3_u32 v35, s78, v35, v39
	v_lshl_or_b32 v0, v34, 7, v0
	v_add3_u32 v43, s40, v36, v37
	v_add3_u32 v36, s78, v36, v39
	v_add_u32_e32 v34, v40, v37
	v_add_u32_e32 v40, v40, v39
	v_add_u32_e32 v37, v41, v37
	v_add_u32_e32 v39, v41, v39
	v_add_u32_e32 v198, v42, v38
	v_add_u32_e32 v199, v35, v38
	v_add_u32_e32 v35, 0x2000, v0
	v_add_u32_e32 v41, 0x4000, v0
	v_add_u32_e32 v42, 0x6000, v0
	v_add_u32_e32 v203, s40, v0
	v_add_u32_e32 v230, s40, v35
	v_add_u32_e32 v231, s40, v41
	v_add_u32_e32 v232, s40, v42
	v_readlane_b32 s40, v254, 58
	v_readlane_b32 s41, v254, 59
	s_mov_b32 s26, 0
	v_add_u32_e32 v200, v43, v38
	v_add_u32_e32 v201, 32, v0
	s_waitcnt lgkmcnt(0)
	s_lshr_b32 s27, s2, 3
	v_add_u32_e32 v202, s78, v0
	v_add_u32_e32 v204, v34, v38
	v_add_u32_e32 v205, v40, v38
	v_add_u32_e32 v206, v37, v38
	v_add_u32_e32 v207, v39, v38
	v_add_u32_e32 v227, s78, v35
	v_add_u32_e32 v228, s78, v41
	v_add_u32_e32 v229, s78, v42
	v_add_u32_e32 v233, v36, v38
	v_readlane_b32 s46, v254, 13
	s_mov_b32 s66, s40
	s_mov_b64 s[40:41], s[42:43]
	s_waitcnt vmcnt(5)
	ds_write_b128 v201, v[2:5]
	ds_write_b128 v201, v[6:9] offset:8192
	s_waitcnt vmcnt(4)
	ds_write_b128 v201, v[10:13] offset:16384
	s_waitcnt vmcnt(3)
	ds_write_b128 v201, v[14:17] offset:24576
	ds_write_b128 v201, v[18:21] offset:32768
	s_waitcnt vmcnt(2)
	ds_write_b128 v201, v[22:25] offset:40960
	s_waitcnt vmcnt(1)
	ds_write_b128 v201, v[26:29] offset:49152
	s_waitcnt vmcnt(0)
	s_mov_b32 s101, 1
	ds_write_b128 v201, v[30:33] offset:57344
	s_branch .LBB0_79

; template <int EPI>
; DI void gemm_phase(const P& p, int l, const u16* __restrict__ A, const u16* __restrict__ Bt, int mpx, char* lds) {
;     ...
;   while (true) {
;   const int tn = t + 1;
;   int m1 = 0, n1 = 0;
;   const bool has_next = tile_coords<EPI>(tn, mpx, m1, n1);
;   const u16* Agn = A + (size_t)m1 * 1024;
;   const u16* Bgn = Bt + (size_t)n1 * 1024;
;   f32x4 acc[8][4];
; #pragma unroll
;   for (int i = 0; i < 8; ++i)
; #pragma unroll
;     for (int j = 0; j < 4; ++j) acc[i][j] = zero4();
;   {
;   const int lane = tid & 63, w = tid >> 6, r = lane & 15, g = lane >> 4, wm = w >> 2, wn = w & 3;
;   __syncthreads();
;   GLOAD(Ag, Bg, 64)
;   __builtin_amdgcn_sched_barrier(0);
;   GCOMPUTE_KS(As0, Bs0, 0)
;   __builtin_amdgcn_sched_barrier(0);
;   GSTORE(As1, Bs1)
;   GLOAD(Ag, Bg, 128)
;   __builtin_amdgcn_sched_barrier(0);
;   GCOMPUTE_KS(As0, Bs0, 1)
;   __builtin_amdgcn_sched_barrier(0);
.LBB0_81:
	s_mov_b32 s57, s3
	s_lshl_b64 s[42:43], s[56:57], 11
	s_lshl_b32 s2, s51, 11
	s_add_u32 s58, s16, s42
	s_addc_u32 s59, s17, s43
	s_add_u32 s60, s24, s2
	s_addc_u32 s61, s25, 0
	v_lshrrev_b32_e32 v166, 3, v195
	v_and_b32_e32 v167, 7, v195
	v_and_b32_e32 v168, 7, v166
	v_xor_b32_e32 v167, v167, v168
	v_lshlrev_b32_e32 v167, 4, v167
	v_lshl_or_b32 v162, v166, 11, v167
	v_add_u32_e32 v163, s33, v162
	v_add_u32_e32 v164, s35, v162
	v_add_u32_e32 v165, s39, v162
	v_readfirstlane_b32 s47, v195
	s_lshr_b32 s47, s47, 6
	s_lshl_b32 s47, s47, 10
	s_and_b32 s48, s84, 7
	s_lshl_b32 s48, s48, 1
	s_mov_b32 s49, 0
	s_waitcnt lgkmcnt(0)
	s_barrier
	s_cmp_eq_u32 s101, 0
	s_cbranch_scc1 .Lrot_in_nofirst
	s_mov_b32 s101, 0
	s_lshl_b32 s2, s48, 7
	s_add_u32 s44, s40, s2
	s_addc_u32 s45, s41, 0
	s_add_u32 s42, s0, s2
	s_addc_u32 s43, s1, 0
	s_add_i32 m0, s47, 0x20
	s_nop 0
	global_load_lds_dwordx4 v162, s[44:45]
	s_add_i32 m0, s47, 0x2020
	s_nop 0
	global_load_lds_dwordx4 v163, s[44:45]
	s_add_i32 m0, s47, 0x4020
	s_nop 0
	global_load_lds_dwordx4 v164, s[44:45]
	s_add_i32 m0, s47, 0x6020
	s_nop 0
	global_load_lds_dwordx4 v165, s[44:45]
	s_add_i32 m0, s47, 0x8020
	s_nop 0
	global_load_lds_dwordx4 v162, s[42:43]
	s_add_i32 m0, s47, 0xa020
	s_nop 0
	global_load_lds_dwordx4 v163, s[42:43]
	s_add_i32 m0, s47, 0xc020
	s_nop 0
	global_load_lds_dwordx4 v164, s[42:43]
	s_add_i32 m0, s47, 0xe020
	s_nop 0
	global_load_lds_dwordx4 v165, s[42:43]
	s_waitcnt vmcnt(0)
	s_barrier
.Lrot_in_nofirst:
	s_add_i32 s48, s48, 1
	s_and_b32 s48, s48, 15
	s_lshl_b32 s2, s48, 7
	s_add_u32 s44, s40, s2
	s_addc_u32 s45, s41, 0
	s_add_u32 s42, s0, s2
	s_addc_u32 s43, s1, 0
	ds_read_b128 v[212:215], v204 offset:32768
	ds_read_b128 v[216:219], v204 offset:34816
	ds_read_b128 v[220:223], v204 offset:36864
	ds_read_b128 v[234:237], v204 offset:38912
	ds_read_b128 v[238:241], v205
	ds_read_b128 v[242:245], v205 offset:2048
	ds_read_b128 v[246:249], v205 offset:4096
	ds_read_b128 v[250:253], v205 offset:6144
	s_waitcnt lgkmcnt(3)
	v_mfma_f32_16x16x32_bf16 v[6:9], v[238:241], v[212:215], 0
	v_mfma_f32_16x16x32_bf16 v[10:13], v[238:241], v[216:219], 0
	v_mfma_f32_16x16x32_bf16 v[14:17], v[238:241], v[220:223], 0
	v_mfma_f32_16x16x32_bf16 v[18:21], v[238:241], v[234:237], 0
	ds_read_b128 v[238:241], v205 offset:8192
	s_add_i32 m0, s47, 0x10020
	s_nop 0
	global_load_lds_dwordx4 v162, s[44:45]
	s_add_i32 m0, s47, 0x12020
	s_nop 0
	global_load_lds_dwordx4 v163, s[44:45]
	s_waitcnt lgkmcnt(3)
	v_mfma_f32_16x16x32_bf16 v[22:25], v[242:245], v[212:215], 0
	v_mfma_f32_16x16x32_bf16 v[26:29], v[242:245], v[216:219], 0
	v_mfma_f32_16x16x32_bf16 v[30:33], v[242:245], v[220:223], 0
	v_mfma_f32_16x16x32_bf16 v[34:37], v[242:245], v[234:237], 0
	ds_read_b128 v[242:245], v205 offset:10240
	ds_read_b128 v[130:133], v206 offset:32768
	s_add_i32 m0, s47, 0x14020
	s_nop 0
	global_load_lds_dwordx4 v164, s[44:45]
	s_add_i32 m0, s47, 0x16020
	s_nop 0
	global_load_lds_dwordx4 v165, s[44:45]
	s_waitcnt lgkmcnt(4)
	v_mfma_f32_16x16x32_bf16 v[38:41], v[246:249], v[212:215], 0
	v_mfma_f32_16x16x32_bf16 v[42:45], v[246:249], v[216:219], 0
	v_mfma_f32_16x16x32_bf16 v[46:49], v[246:249], v[220:223], 0
	v_mfma_f32_16x16x32_bf16 v[50:53], v[246:249], v[234:237], 0
	ds_read_b128 v[246:249], v205 offset:12288
	ds_read_b128 v[134:137], v206 offset:34816
	s_add_i32 m0, s47, 0x18020
	s_nop 0
	global_load_lds_dwordx4 v162, s[42:43]
	s_add_i32 m0, s47, 0x1a020
	s_nop 0
	global_load_lds_dwordx4 v163, s[42:43]
	s_waitcnt lgkmcnt(5)
	v_mfma_f32_16x16x32_bf16 v[54:57], v[250:253], v[212:215], 0
	v_mfma_f32_16x16x32_bf16 v[58:61], v[250:253], v[216:219], 0
	v_mfma_f32_16x16x32_bf16 v[62:65], v[250:253], v[220:223], 0
	v_mfma_f32_16x16x32_bf16 v[66:69], v[250:253], v[234:237], 0
	ds_read_b128 v[250:253], v205 offset:14336
	ds_read_b128 v[138:141], v206 offset:36864
	s_add_i32 m0, s47, 0x1c020
	s_nop 0
	global_load_lds_dwordx4 v164, s[42:43]
	s_add_i32 m0, s47, 0x1e020
	s_nop 0
	global_load_lds_dwordx4 v165, s[42:43]
	s_waitcnt lgkmcnt(6)
	v_mfma_f32_16x16x32_bf16 v[70:73], v[238:241], v[212:215], 0
	v_mfma_f32_16x16x32_bf16 v[74:77], v[238:241], v[216:219], 0
	v_mfma_f32_16x16x32_bf16 v[78:81], v[238:241], v[220:223], 0
	v_mfma_f32_16x16x32_bf16 v[82:85], v[238:241], v[234:237], 0
	ds_read_b128 v[238:241], v207
	ds_read_b128 v[142:145], v206 offset:38912
	s_waitcnt lgkmcnt(7)
	v_mfma_f32_16x16x32_bf16 v[86:89], v[242:245], v[212:215], 0
	v_mfma_f32_16x16x32_bf16 v[90:93], v[242:245], v[216:219], 0
	v_mfma_f32_16x16x32_bf16 v[94:97], v[242:245], v[220:223], 0
	v_mfma_f32_16x16x32_bf16 v[98:101], v[242:245], v[234:237], 0
	ds_read_b128 v[242:245], v207 offset:2048
	s_waitcnt lgkmcnt(6)
	v_mfma_f32_16x16x32_bf16 v[102:105], v[246:249], v[212:215], 0
	v_mfma_f32_16x16x32_bf16 v[106:109], v[246:249], v[216:219], 0
	v_mfma_f32_16x16x32_bf16 v[110:113], v[246:249], v[220:223], 0
	v_mfma_f32_16x16x32_bf16 v[114:117], v[246:249], v[234:237], 0
	ds_read_b128 v[246:249], v207 offset:4096
	s_waitcnt lgkmcnt(5)
	v_mfma_f32_16x16x32_bf16 v[118:121], v[250:253], v[212:215], 0
	v_mfma_f32_16x16x32_bf16 v[122:125], v[250:253], v[216:219], 0
	v_mfma_f32_16x16x32_bf16 v[126:129], v[250:253], v[220:223], 0
	v_mfma_f32_16x16x32_bf16 v[2:5], v[250:253], v[234:237], 0
	ds_read_b128 v[250:253], v207 offset:6144
	s_waitcnt lgkmcnt(3)
	v_mfma_f32_16x16x32_bf16 v[6:9], v[238:241], v[130:133], v[6:9]
	v_mfma_f32_16x16x32_bf16 v[10:13], v[238:241], v[134:137], v[10:13]
	v_mfma_f32_16x16x32_bf16 v[14:17], v[238:241], v[138:141], v[14:17]
	v_mfma_f32_16x16x32_bf16 v[18:21], v[238:241], v[142:145], v[18:21]
	ds_read_b128 v[238:241], v207 offset:8192
	s_waitcnt lgkmcnt(3)
; #define GCOMPUTE(AS, BS) GCOMPUTE_KS(AS, BS, 0) GCOMPUTE_KS(AS, BS, 1)
; template <int EPI>
; DI void gemm_phase(const P& p, int l, const u16* __restrict__ A, const u16* __restrict__ Bt, int mpx, char* lds) {
;     ...
;   GCOMPUTE_KS(As0, Bs0, 0)
;   __builtin_amdgcn_sched_barrier(0);
;   GSTORE(As1, Bs1)
;   GLOAD(Ag, Bg, 128)
;   __builtin_amdgcn_sched_barrier(0);
;   GCOMPUTE_KS(As0, Bs0, 1)
;   __builtin_amdgcn_sched_barrier(0);
; #pragma unroll 1
;   for (int kk = 1; kk < 15; kk += 2) {
;     __syncthreads();
;     GSTORE(As0, Bs0)
;     GLOAD(Ag, Bg, (kk + 2) * 64)
;     __builtin_amdgcn_sched_barrier(0);
;     GCOMPUTE(As1, Bs1)
;     __builtin_amdgcn_sched_barrier(0);
;     __syncthreads();
;     GSTORE(As1, Bs1)
	v_mfma_f32_16x16x32_bf16 v[22:25], v[242:245], v[130:133], v[22:25]
	v_mfma_f32_16x16x32_bf16 v[26:29], v[242:245], v[134:137], v[26:29]
	v_mfma_f32_16x16x32_bf16 v[30:33], v[242:245], v[138:141], v[30:33]
	v_mfma_f32_16x16x32_bf16 v[34:37], v[242:245], v[142:145], v[34:37]
	ds_read_b128 v[242:245], v207 offset:10240
	s_waitcnt lgkmcnt(3)
	v_mfma_f32_16x16x32_bf16 v[38:41], v[246:249], v[130:133], v[38:41]
	v_mfma_f32_16x16x32_bf16 v[42:45], v[246:249], v[134:137], v[42:45]
	v_mfma_f32_16x16x32_bf16 v[46:49], v[246:249], v[138:141], v[46:49]
	v_mfma_f32_16x16x32_bf16 v[50:53], v[246:249], v[142:145], v[50:53]
	ds_read_b128 v[246:249], v207 offset:12288
	s_waitcnt lgkmcnt(3)
	v_mfma_f32_16x16x32_bf16 v[54:57], v[250:253], v[130:133], v[54:57]
	v_mfma_f32_16x16x32_bf16 v[58:61], v[250:253], v[134:137], v[58:61]
	v_mfma_f32_16x16x32_bf16 v[62:65], v[250:253], v[138:141], v[62:65]
	v_mfma_f32_16x16x32_bf16 v[66:69], v[250:253], v[142:145], v[66:69]
	ds_read_b128 v[250:253], v207 offset:14336
	s_waitcnt lgkmcnt(3)
	v_mfma_f32_16x16x32_bf16 v[70:73], v[238:241], v[130:133], v[70:73]
	v_mfma_f32_16x16x32_bf16 v[74:77], v[238:241], v[134:137], v[74:77]
	v_mfma_f32_16x16x32_bf16 v[78:81], v[238:241], v[138:141], v[78:81]
	v_mfma_f32_16x16x32_bf16 v[82:85], v[238:241], v[142:145], v[82:85]
	s_waitcnt lgkmcnt(2)
	v_mfma_f32_16x16x32_bf16 v[86:89], v[242:245], v[130:133], v[86:89]
	v_mfma_f32_16x16x32_bf16 v[90:93], v[242:245], v[134:137], v[90:93]
	v_mfma_f32_16x16x32_bf16 v[94:97], v[242:245], v[138:141], v[94:97]
	v_mfma_f32_16x16x32_bf16 v[98:101], v[242:245], v[142:145], v[98:101]
	s_waitcnt lgkmcnt(0)
	s_waitcnt vmcnt(0)
	s_add_i32 s48, s48, 1
	s_and_b32 s48, s48, 15
	s_lshl_b32 s2, s48, 7
	s_add_u32 s44, s40, s2
	s_addc_u32 s45, s41, 0
	s_add_u32 s42, s0, s2
	s_addc_u32 s43, s1, 0
	s_barrier
	ds_read_b128 v[212:215], v198
	ds_read_b128 v[216:219], v198 offset:2048
	ds_read_b128 v[220:223], v198 offset:4096
	ds_read_b128 v[234:237], v198 offset:6144
	ds_read_b128 v[238:241], v199
	ds_read_b128 v[242:245], v199 offset:2048
	v_mfma_f32_16x16x32_bf16 v[102:105], v[246:249], v[130:133], v[102:105]
	v_mfma_f32_16x16x32_bf16 v[106:109], v[246:249], v[134:137], v[106:109]
	v_mfma_f32_16x16x32_bf16 v[110:113], v[246:249], v[138:141], v[110:113]
	v_mfma_f32_16x16x32_bf16 v[114:117], v[246:249], v[142:145], v[114:117]
	ds_read_b128 v[246:249], v199 offset:4096
	v_mfma_f32_16x16x32_bf16 v[118:121], v[250:253], v[130:133], v[118:121]
	v_mfma_f32_16x16x32_bf16 v[122:125], v[250:253], v[134:137], v[122:125]
	v_mfma_f32_16x16x32_bf16 v[126:129], v[250:253], v[138:141], v[126:129]
	v_mfma_f32_16x16x32_bf16 v[2:5], v[250:253], v[142:145], v[2:5]
	ds_read_b128 v[250:253], v199 offset:6144
.LBB0_82:
	s_waitcnt lgkmcnt(3)
	v_mfma_f32_16x16x32_bf16 v[6:9], v[238:241], v[212:215], v[6:9]
	v_mfma_f32_16x16x32_bf16 v[10:13], v[238:241], v[216:219], v[10:13]
	v_mfma_f32_16x16x32_bf16 v[14:17], v[238:241], v[220:223], v[14:17]
	v_mfma_f32_16x16x32_bf16 v[18:21], v[238:241], v[234:237], v[18:21]
	ds_read_b128 v[238:241], v199 offset:8192
	s_add_i32 m0, s47, 0x20
	s_nop 0
	global_load_lds_dwordx4 v162, s[44:45]
	s_add_i32 m0, s47, 0x2020
	s_nop 0
	global_load_lds_dwordx4 v163, s[44:45]
	s_waitcnt lgkmcnt(3)
	v_mfma_f32_16x16x32_bf16 v[22:25], v[242:245], v[212:215], v[22:25]
	v_mfma_f32_16x16x32_bf16 v[26:29], v[242:245], v[216:219], v[26:29]
	v_mfma_f32_16x16x32_bf16 v[30:33], v[242:245], v[220:223], v[30:33]
	v_mfma_f32_16x16x32_bf16 v[34:37], v[242:245], v[234:237], v[34:37]
	ds_read_b128 v[242:245], v199 offset:10240
	ds_read_b128 v[130:133], v200
	s_add_i32 m0, s47, 0x4020
	s_nop 0
	global_load_lds_dwordx4 v164, s[44:45]
	s_add_i32 m0, s47, 0x6020
	s_nop 0
	global_load_lds_dwordx4 v165, s[44:45]
	s_waitcnt lgkmcnt(4)
	v_mfma_f32_16x16x32_bf16 v[38:41], v[246:249], v[212:215], v[38:41]
	v_mfma_f32_16x16x32_bf16 v[42:45], v[246:249], v[216:219], v[42:45]
	v_mfma_f32_16x16x32_bf16 v[46:49], v[246:249], v[220:223], v[46:49]
	v_mfma_f32_16x16x32_bf16 v[50:53], v[246:249], v[234:237], v[50:53]
	ds_read_b128 v[246:249], v199 offset:12288
	ds_read_b128 v[134:137], v200 offset:2048
	s_add_i32 m0, s47, 0x8020
	s_nop 0
	global_load_lds_dwordx4 v162, s[42:43]
	s_add_i32 m0, s47, 0xa020
	s_nop 0
	global_load_lds_dwordx4 v163, s[42:43]
	s_waitcnt lgkmcnt(5)
	v_mfma_f32_16x16x32_bf16 v[54:57], v[250:253], v[212:215], v[54:57]
	v_mfma_f32_16x16x32_bf16 v[58:61], v[250:253], v[216:219], v[58:61]
	v_mfma_f32_16x16x32_bf16 v[62:65], v[250:253], v[220:223], v[62:65]
	v_mfma_f32_16x16x32_bf16 v[66:69], v[250:253], v[234:237], v[66:69]
	ds_read_b128 v[250:253], v199 offset:14336
	ds_read_b128 v[138:141], v200 offset:4096
	s_add_i32 m0, s47, 0xc020
	s_nop 0
	global_load_lds_dwordx4 v164, s[42:43]
	s_add_i32 m0, s47, 0xe020
	s_nop 0
	global_load_lds_dwordx4 v165, s[42:43]
	s_waitcnt lgkmcnt(6)
	v_mfma_f32_16x16x32_bf16 v[70:73], v[238:241], v[212:215], v[70:73]
	v_mfma_f32_16x16x32_bf16 v[74:77], v[238:241], v[216:219], v[74:77]
	v_mfma_f32_16x16x32_bf16 v[78:81], v[238:241], v[220:223], v[78:81]
	v_mfma_f32_16x16x32_bf16 v[82:85], v[238:241], v[234:237], v[82:85]
	ds_read_b128 v[238:241], v233
	ds_read_b128 v[142:145], v200 offset:6144
	s_waitcnt lgkmcnt(7)
	v_mfma_f32_16x16x32_bf16 v[86:89], v[242:245], v[212:215], v[86:89]
	v_mfma_f32_16x16x32_bf16 v[90:93], v[242:245], v[216:219], v[90:93]
	v_mfma_f32_16x16x32_bf16 v[94:97], v[242:245], v[220:223], v[94:97]
	v_mfma_f32_16x16x32_bf16 v[98:101], v[242:245], v[234:237], v[98:101]
	ds_read_b128 v[242:245], v233 offset:2048
	s_waitcnt lgkmcnt(6)
; #define GCOMPUTE(AS, BS) GCOMPUTE_KS(AS, BS, 0) GCOMPUTE_KS(AS, BS, 1)
; template <int EPI>
; DI void gemm_phase(const P& p, int l, const u16* __restrict__ A, const u16* __restrict__ Bt, int mpx, char* lds) {
;     ...
;   for (int kk = 1; kk < 15; kk += 2) {
;     __syncthreads();
;     GSTORE(As0, Bs0)
;     GLOAD(Ag, Bg, (kk + 2) * 64)
;     __builtin_amdgcn_sched_barrier(0);
;     GCOMPUTE(As1, Bs1)
;     __builtin_amdgcn_sched_barrier(0);
;     __syncthreads();
;     GSTORE(As1, Bs1)
;     {
;       const bool in_tile = kk + 3 < 16;
;       const u16* pa = in_tile ? Ag : Agn;
;       const u16* pb = in_tile ? Bg : Bgn;
;       const int k0 = in_tile ? (kk + 3) * 64 : 0;
;       GLOAD(pa, pb, k0)
;     }
;     __builtin_amdgcn_sched_barrier(0);
;     GCOMPUTE(As0, Bs0)
	v_mfma_f32_16x16x32_bf16 v[102:105], v[246:249], v[212:215], v[102:105]
	v_mfma_f32_16x16x32_bf16 v[106:109], v[246:249], v[216:219], v[106:109]
	v_mfma_f32_16x16x32_bf16 v[110:113], v[246:249], v[220:223], v[110:113]
	v_mfma_f32_16x16x32_bf16 v[114:117], v[246:249], v[234:237], v[114:117]
	ds_read_b128 v[246:249], v233 offset:4096
	s_waitcnt lgkmcnt(5)
	v_mfma_f32_16x16x32_bf16 v[118:121], v[250:253], v[212:215], v[118:121]
	v_mfma_f32_16x16x32_bf16 v[122:125], v[250:253], v[216:219], v[122:125]
	v_mfma_f32_16x16x32_bf16 v[126:129], v[250:253], v[220:223], v[126:129]
	v_mfma_f32_16x16x32_bf16 v[2:5], v[250:253], v[234:237], v[2:5]
	ds_read_b128 v[250:253], v233 offset:6144
	s_waitcnt lgkmcnt(3)
	v_mfma_f32_16x16x32_bf16 v[6:9], v[238:241], v[130:133], v[6:9]
	v_mfma_f32_16x16x32_bf16 v[10:13], v[238:241], v[134:137], v[10:13]
	v_mfma_f32_16x16x32_bf16 v[14:17], v[238:241], v[138:141], v[14:17]
	v_mfma_f32_16x16x32_bf16 v[18:21], v[238:241], v[142:145], v[18:21]
	ds_read_b128 v[238:241], v233 offset:8192
	s_waitcnt lgkmcnt(3)
	v_mfma_f32_16x16x32_bf16 v[22:25], v[242:245], v[130:133], v[22:25]
	v_mfma_f32_16x16x32_bf16 v[26:29], v[242:245], v[134:137], v[26:29]
	v_mfma_f32_16x16x32_bf16 v[30:33], v[242:245], v[138:141], v[30:33]
	v_mfma_f32_16x16x32_bf16 v[34:37], v[242:245], v[142:145], v[34:37]
	ds_read_b128 v[242:245], v233 offset:10240
	s_waitcnt lgkmcnt(3)
	v_mfma_f32_16x16x32_bf16 v[38:41], v[246:249], v[130:133], v[38:41]
	v_mfma_f32_16x16x32_bf16 v[42:45], v[246:249], v[134:137], v[42:45]
	v_mfma_f32_16x16x32_bf16 v[46:49], v[246:249], v[138:141], v[46:49]
	v_mfma_f32_16x16x32_bf16 v[50:53], v[246:249], v[142:145], v[50:53]
	ds_read_b128 v[246:249], v233 offset:12288
	s_waitcnt lgkmcnt(3)
	v_mfma_f32_16x16x32_bf16 v[54:57], v[250:253], v[130:133], v[54:57]
	v_mfma_f32_16x16x32_bf16 v[58:61], v[250:253], v[134:137], v[58:61]
	v_mfma_f32_16x16x32_bf16 v[62:65], v[250:253], v[138:141], v[62:65]
	v_mfma_f32_16x16x32_bf16 v[66:69], v[250:253], v[142:145], v[66:69]
	ds_read_b128 v[250:253], v233 offset:14336
	s_waitcnt lgkmcnt(3)
	v_mfma_f32_16x16x32_bf16 v[70:73], v[238:241], v[130:133], v[70:73]
	v_mfma_f32_16x16x32_bf16 v[74:77], v[238:241], v[134:137], v[74:77]
	v_mfma_f32_16x16x32_bf16 v[78:81], v[238:241], v[138:141], v[78:81]
	v_mfma_f32_16x16x32_bf16 v[82:85], v[238:241], v[142:145], v[82:85]
	s_waitcnt lgkmcnt(2)
	v_mfma_f32_16x16x32_bf16 v[86:89], v[242:245], v[130:133], v[86:89]
	v_mfma_f32_16x16x32_bf16 v[90:93], v[242:245], v[134:137], v[90:93]
	v_mfma_f32_16x16x32_bf16 v[94:97], v[242:245], v[138:141], v[94:97]
	v_mfma_f32_16x16x32_bf16 v[98:101], v[242:245], v[142:145], v[98:101]
	s_waitcnt lgkmcnt(0)
	s_waitcnt vmcnt(0)
	s_add_i32 s48, s48, 1
	s_and_b32 s48, s48, 15
	s_lshl_b32 s2, s48, 7
	s_add_u32 s44, s40, s2
	s_addc_u32 s45, s41, 0
	s_add_u32 s42, s0, s2
	s_addc_u32 s43, s1, 0
	s_barrier
	ds_read_b128 v[212:215], v204 offset:32768
	ds_read_b128 v[216:219], v204 offset:34816
	ds_read_b128 v[220:223], v204 offset:36864
	ds_read_b128 v[234:237], v204 offset:38912
	ds_read_b128 v[238:241], v205
	ds_read_b128 v[242:245], v205 offset:2048
	v_mfma_f32_16x16x32_bf16 v[102:105], v[246:249], v[130:133], v[102:105]
	v_mfma_f32_16x16x32_bf16 v[106:109], v[246:249], v[134:137], v[106:109]
	v_mfma_f32_16x16x32_bf16 v[110:113], v[246:249], v[138:141], v[110:113]
	v_mfma_f32_16x16x32_bf16 v[114:117], v[246:249], v[142:145], v[114:117]
	ds_read_b128 v[246:249], v205 offset:4096
	v_mfma_f32_16x16x32_bf16 v[118:121], v[250:253], v[130:133], v[118:121]
	v_mfma_f32_16x16x32_bf16 v[122:125], v[250:253], v[134:137], v[122:125]
	v_mfma_f32_16x16x32_bf16 v[126:129], v[250:253], v[138:141], v[126:129]
	v_mfma_f32_16x16x32_bf16 v[2:5], v[250:253], v[142:145], v[2:5]
	ds_read_b128 v[250:253], v205 offset:6144
	s_waitcnt lgkmcnt(3)
	v_mfma_f32_16x16x32_bf16 v[6:9], v[238:241], v[212:215], v[6:9]
	v_mfma_f32_16x16x32_bf16 v[10:13], v[238:241], v[216:219], v[10:13]
	v_mfma_f32_16x16x32_bf16 v[14:17], v[238:241], v[220:223], v[14:17]
	v_mfma_f32_16x16x32_bf16 v[18:21], v[238:241], v[234:237], v[18:21]
	ds_read_b128 v[238:241], v205 offset:8192
	s_add_i32 m0, s47, 0x10020
	s_nop 0
	global_load_lds_dwordx4 v162, s[44:45]
	s_add_i32 m0, s47, 0x12020
	s_nop 0
	global_load_lds_dwordx4 v163, s[44:45]
	s_waitcnt lgkmcnt(3)
	v_mfma_f32_16x16x32_bf16 v[22:25], v[242:245], v[212:215], v[22:25]
	v_mfma_f32_16x16x32_bf16 v[26:29], v[242:245], v[216:219], v[26:29]
	v_mfma_f32_16x16x32_bf16 v[30:33], v[242:245], v[220:223], v[30:33]
	v_mfma_f32_16x16x32_bf16 v[34:37], v[242:245], v[234:237], v[34:37]
	ds_read_b128 v[242:245], v205 offset:10240
	ds_read_b128 v[130:133], v206 offset:32768
	s_add_i32 m0, s47, 0x14020
	s_nop 0
	global_load_lds_dwordx4 v164, s[44:45]
	s_add_i32 m0, s47, 0x16020
	s_nop 0
	global_load_lds_dwordx4 v165, s[44:45]
	s_waitcnt lgkmcnt(4)
	v_mfma_f32_16x16x32_bf16 v[38:41], v[246:249], v[212:215], v[38:41]
	v_mfma_f32_16x16x32_bf16 v[42:45], v[246:249], v[216:219], v[42:45]
	v_mfma_f32_16x16x32_bf16 v[46:49], v[246:249], v[220:223], v[46:49]
	v_mfma_f32_16x16x32_bf16 v[50:53], v[246:249], v[234:237], v[50:53]
	ds_read_b128 v[246:249], v205 offset:12288
	ds_read_b128 v[134:137], v206 offset:34816
	s_add_i32 m0, s47, 0x18020
	s_nop 0
	global_load_lds_dwordx4 v162, s[42:43]
	s_add_i32 m0, s47, 0x1a020
	s_nop 0
	global_load_lds_dwordx4 v163, s[42:43]
	s_waitcnt lgkmcnt(5)
	v_mfma_f32_16x16x32_bf16 v[54:57], v[250:253], v[212:215], v[54:57]
	v_mfma_f32_16x16x32_bf16 v[58:61], v[250:253], v[216:219], v[58:61]
	v_mfma_f32_16x16x32_bf16 v[62:65], v[250:253], v[220:223], v[62:65]
	v_mfma_f32_16x16x32_bf16 v[66:69], v[250:253], v[234:237], v[66:69]
	ds_read_b128 v[250:253], v205 offset:14336
	ds_read_b128 v[138:141], v206 offset:36864
	s_add_i32 m0, s47, 0x1c020
	s_nop 0
	global_load_lds_dwordx4 v164, s[42:43]
	s_add_i32 m0, s47, 0x1e020
	s_nop 0
	global_load_lds_dwordx4 v165, s[42:43]
	s_waitcnt lgkmcnt(6)
; #define GCOMPUTE(AS, BS) GCOMPUTE_KS(AS, BS, 0) GCOMPUTE_KS(AS, BS, 1)
; template <int EPI>
; DI void gemm_phase(const P& p, int l, const u16* __restrict__ A, const u16* __restrict__ Bt, int mpx, char* lds) {
;     ...
;     __syncthreads();
;     GSTORE(As1, Bs1)
;     {
;       const bool in_tile = kk + 3 < 16;
;       const u16* pa = in_tile ? Ag : Agn;
;       const u16* pb = in_tile ? Bg : Bgn;
;       const int k0 = in_tile ? (kk + 3) * 64 : 0;
;       GLOAD(pa, pb, k0)
;     }
;     __builtin_amdgcn_sched_barrier(0);
;     GCOMPUTE(As0, Bs0)
;     __builtin_amdgcn_sched_barrier(0);
;   }
	v_mfma_f32_16x16x32_bf16 v[70:73], v[238:241], v[212:215], v[70:73]
	v_mfma_f32_16x16x32_bf16 v[74:77], v[238:241], v[216:219], v[74:77]
	v_mfma_f32_16x16x32_bf16 v[78:81], v[238:241], v[220:223], v[78:81]
	v_mfma_f32_16x16x32_bf16 v[82:85], v[238:241], v[234:237], v[82:85]
	ds_read_b128 v[238:241], v207
	ds_read_b128 v[142:145], v206 offset:38912
	s_waitcnt lgkmcnt(7)
	v_mfma_f32_16x16x32_bf16 v[86:89], v[242:245], v[212:215], v[86:89]
	v_mfma_f32_16x16x32_bf16 v[90:93], v[242:245], v[216:219], v[90:93]
	v_mfma_f32_16x16x32_bf16 v[94:97], v[242:245], v[220:223], v[94:97]
	v_mfma_f32_16x16x32_bf16 v[98:101], v[242:245], v[234:237], v[98:101]
	ds_read_b128 v[242:245], v207 offset:2048
	s_waitcnt lgkmcnt(6)
	v_mfma_f32_16x16x32_bf16 v[102:105], v[246:249], v[212:215], v[102:105]
	v_mfma_f32_16x16x32_bf16 v[106:109], v[246:249], v[216:219], v[106:109]
	v_mfma_f32_16x16x32_bf16 v[110:113], v[246:249], v[220:223], v[110:113]
	v_mfma_f32_16x16x32_bf16 v[114:117], v[246:249], v[234:237], v[114:117]
	ds_read_b128 v[246:249], v207 offset:4096
	s_waitcnt lgkmcnt(5)
	v_mfma_f32_16x16x32_bf16 v[118:121], v[250:253], v[212:215], v[118:121]
	v_mfma_f32_16x16x32_bf16 v[122:125], v[250:253], v[216:219], v[122:125]
	v_mfma_f32_16x16x32_bf16 v[126:129], v[250:253], v[220:223], v[126:129]
	v_mfma_f32_16x16x32_bf16 v[2:5], v[250:253], v[234:237], v[2:5]
	ds_read_b128 v[250:253], v207 offset:6144
	s_waitcnt lgkmcnt(3)
	v_mfma_f32_16x16x32_bf16 v[6:9], v[238:241], v[130:133], v[6:9]
	v_mfma_f32_16x16x32_bf16 v[10:13], v[238:241], v[134:137], v[10:13]
	v_mfma_f32_16x16x32_bf16 v[14:17], v[238:241], v[138:141], v[14:17]
	v_mfma_f32_16x16x32_bf16 v[18:21], v[238:241], v[142:145], v[18:21]
	ds_read_b128 v[238:241], v207 offset:8192
	s_waitcnt lgkmcnt(3)
	v_mfma_f32_16x16x32_bf16 v[22:25], v[242:245], v[130:133], v[22:25]
	v_mfma_f32_16x16x32_bf16 v[26:29], v[242:245], v[134:137], v[26:29]
	v_mfma_f32_16x16x32_bf16 v[30:33], v[242:245], v[138:141], v[30:33]
	v_mfma_f32_16x16x32_bf16 v[34:37], v[242:245], v[142:145], v[34:37]
	ds_read_b128 v[242:245], v207 offset:10240
	s_waitcnt lgkmcnt(3)
	v_mfma_f32_16x16x32_bf16 v[38:41], v[246:249], v[130:133], v[38:41]
	v_mfma_f32_16x16x32_bf16 v[42:45], v[246:249], v[134:137], v[42:45]
	v_mfma_f32_16x16x32_bf16 v[46:49], v[246:249], v[138:141], v[46:49]
	v_mfma_f32_16x16x32_bf16 v[50:53], v[246:249], v[142:145], v[50:53]
	ds_read_b128 v[246:249], v207 offset:12288
	s_waitcnt lgkmcnt(3)
	v_mfma_f32_16x16x32_bf16 v[54:57], v[250:253], v[130:133], v[54:57]
	v_mfma_f32_16x16x32_bf16 v[58:61], v[250:253], v[134:137], v[58:61]
	v_mfma_f32_16x16x32_bf16 v[62:65], v[250:253], v[138:141], v[62:65]
	v_mfma_f32_16x16x32_bf16 v[66:69], v[250:253], v[142:145], v[66:69]
	ds_read_b128 v[250:253], v207 offset:14336
	s_waitcnt lgkmcnt(3)
	v_mfma_f32_16x16x32_bf16 v[70:73], v[238:241], v[130:133], v[70:73]
	v_mfma_f32_16x16x32_bf16 v[74:77], v[238:241], v[134:137], v[74:77]
	v_mfma_f32_16x16x32_bf16 v[78:81], v[238:241], v[138:141], v[78:81]
	v_mfma_f32_16x16x32_bf16 v[82:85], v[238:241], v[142:145], v[82:85]
	s_waitcnt lgkmcnt(2)
	v_mfma_f32_16x16x32_bf16 v[86:89], v[242:245], v[130:133], v[86:89]
	v_mfma_f32_16x16x32_bf16 v[90:93], v[242:245], v[134:137], v[90:93]
	v_mfma_f32_16x16x32_bf16 v[94:97], v[242:245], v[138:141], v[94:97]
	v_mfma_f32_16x16x32_bf16 v[98:101], v[242:245], v[142:145], v[98:101]
	s_waitcnt lgkmcnt(0)
	s_waitcnt vmcnt(0)
	s_add_i32 s48, s48, 1
	s_and_b32 s48, s48, 15
	s_lshl_b32 s2, s48, 7
	s_add_u32 s44, s40, s2
	s_addc_u32 s45, s41, 0
	s_add_u32 s42, s0, s2
	s_addc_u32 s43, s1, 0
	s_add_i32 s49, s49, 1
	s_cmp_lt_u32 s49, 7
	s_barrier
	ds_read_b128 v[212:215], v198
	ds_read_b128 v[216:219], v198 offset:2048
	ds_read_b128 v[220:223], v198 offset:4096
	ds_read_b128 v[234:237], v198 offset:6144
	ds_read_b128 v[238:241], v199
	ds_read_b128 v[242:245], v199 offset:2048
	v_mfma_f32_16x16x32_bf16 v[102:105], v[246:249], v[130:133], v[102:105]
	v_mfma_f32_16x16x32_bf16 v[106:109], v[246:249], v[134:137], v[106:109]
	v_mfma_f32_16x16x32_bf16 v[110:113], v[246:249], v[138:141], v[110:113]
	v_mfma_f32_16x16x32_bf16 v[114:117], v[246:249], v[142:145], v[114:117]
	ds_read_b128 v[246:249], v199 offset:4096
	v_mfma_f32_16x16x32_bf16 v[118:121], v[250:253], v[130:133], v[118:121]
	v_mfma_f32_16x16x32_bf16 v[122:125], v[250:253], v[134:137], v[122:125]
	v_mfma_f32_16x16x32_bf16 v[126:129], v[250:253], v[138:141], v[126:129]
	v_mfma_f32_16x16x32_bf16 v[2:5], v[250:253], v[142:145], v[2:5]
	ds_read_b128 v[250:253], v199 offset:6144
	s_cbranch_scc1 .LBB0_82
; #define GCOMPUTE(AS, BS) GCOMPUTE_KS(AS, BS, 0) GCOMPUTE_KS(AS, BS, 1)
; template <int EPI>
; DI void gemm_phase(const P& p, int l, const u16* __restrict__ A, const u16* __restrict__ Bt, int mpx, char* lds) {
;     ...
;   }
;   __syncthreads();
;   __builtin_amdgcn_sched_barrier(0);
;   GCOMPUTE(As1, Bs1)
;   __builtin_amdgcn_sched_barrier(0);
;   }
;   __syncthreads();
;   GSTORE(As0, Bs0)
;     ...
;     const int cb = n0 + wn * 64;
;     const bool isctx = m0 >= MLAT;
;     const int b = isctx ? ((m0 - MLAT) >> 8) : (m0 >> 11);
;     const int tokw = (isctx ? 2048 + ((m0 - MLAT) & 255) : (m0 & 2047)) + wm * 128;
;     u16* Tl = (u16*)(lds + 65536) + w * (64 * 72);
;     int kind = 0;
;     int tr = 0;
;     bool donorm = false;
;     if (cb >= 2816) { kind = 2; tr = 1; }
;     else if (cb < 256) tr = 1;
;     else if (cb < 512) tr = 0;
;     else if (cb < 1024) tr = 2;
;     else if (cb < 1408) { tr = 3; donorm = true; }
;     else if (cb < 1536) kind = 1;
;     else if (cb < 2048) tr = isctx ? 0 : 4;
;     else if (cb < 2304) kind = 1;
;     else if (cb < 2688) tr = isctx ? 0 : 3;
;     else kind = 1;
	s_and_b32 s2, s84, 7
	s_lshl_b32 s2, s2, 8
	s_add_u32 s44, s58, s2
	s_addc_u32 s45, s59, 0
	s_add_u32 s42, s60, s2
	s_addc_u32 s43, s61, 0
	s_waitcnt lgkmcnt(3)
	v_mfma_f32_16x16x32_bf16 v[6:9], v[238:241], v[212:215], v[6:9]
	v_mfma_f32_16x16x32_bf16 v[10:13], v[238:241], v[216:219], v[10:13]
	v_mfma_f32_16x16x32_bf16 v[14:17], v[238:241], v[220:223], v[14:17]
	v_mfma_f32_16x16x32_bf16 v[18:21], v[238:241], v[234:237], v[18:21]
	ds_read_b128 v[238:241], v199 offset:8192
	s_add_i32 m0, s47, 0x20
	s_nop 0
	global_load_lds_dwordx4 v162, s[44:45]
	s_add_i32 m0, s47, 0x2020
	s_nop 0
	global_load_lds_dwordx4 v163, s[44:45]
	s_waitcnt lgkmcnt(3)
	v_mfma_f32_16x16x32_bf16 v[22:25], v[242:245], v[212:215], v[22:25]
	v_mfma_f32_16x16x32_bf16 v[26:29], v[242:245], v[216:219], v[26:29]
	v_mfma_f32_16x16x32_bf16 v[30:33], v[242:245], v[220:223], v[30:33]
	v_mfma_f32_16x16x32_bf16 v[34:37], v[242:245], v[234:237], v[34:37]
	ds_read_b128 v[242:245], v199 offset:10240
	ds_read_b128 v[130:133], v200
	s_add_i32 m0, s47, 0x4020
	s_nop 0
	global_load_lds_dwordx4 v164, s[44:45]
	s_add_i32 m0, s47, 0x6020
	s_nop 0
	global_load_lds_dwordx4 v165, s[44:45]
	s_waitcnt lgkmcnt(4)
	v_mfma_f32_16x16x32_bf16 v[38:41], v[246:249], v[212:215], v[38:41]
	v_mfma_f32_16x16x32_bf16 v[42:45], v[246:249], v[216:219], v[42:45]
	v_mfma_f32_16x16x32_bf16 v[46:49], v[246:249], v[220:223], v[46:49]
	v_mfma_f32_16x16x32_bf16 v[50:53], v[246:249], v[234:237], v[50:53]
	ds_read_b128 v[246:249], v199 offset:12288
	ds_read_b128 v[134:137], v200 offset:2048
	s_add_i32 m0, s47, 0x8020
	s_nop 0
	global_load_lds_dwordx4 v162, s[42:43]
	s_add_i32 m0, s47, 0xa020
	s_nop 0
	global_load_lds_dwordx4 v163, s[42:43]
	s_waitcnt lgkmcnt(5)
	v_mfma_f32_16x16x32_bf16 v[54:57], v[250:253], v[212:215], v[54:57]
	v_mfma_f32_16x16x32_bf16 v[58:61], v[250:253], v[216:219], v[58:61]
	v_mfma_f32_16x16x32_bf16 v[62:65], v[250:253], v[220:223], v[62:65]
	v_mfma_f32_16x16x32_bf16 v[66:69], v[250:253], v[234:237], v[66:69]
	ds_read_b128 v[250:253], v199 offset:14336
	ds_read_b128 v[138:141], v200 offset:4096
	s_add_i32 m0, s47, 0xc020
	s_nop 0
	global_load_lds_dwordx4 v164, s[42:43]
	s_add_i32 m0, s47, 0xe020
	s_nop 0
	global_load_lds_dwordx4 v165, s[42:43]
	s_waitcnt lgkmcnt(6)
	v_mfma_f32_16x16x32_bf16 v[70:73], v[238:241], v[212:215], v[70:73]
	v_mfma_f32_16x16x32_bf16 v[74:77], v[238:241], v[216:219], v[74:77]
	v_mfma_f32_16x16x32_bf16 v[78:81], v[238:241], v[220:223], v[78:81]
	v_mfma_f32_16x16x32_bf16 v[82:85], v[238:241], v[234:237], v[82:85]
	ds_read_b128 v[238:241], v233
	ds_read_b128 v[142:145], v200 offset:6144
	s_waitcnt lgkmcnt(7)
	v_mfma_f32_16x16x32_bf16 v[86:89], v[242:245], v[212:215], v[86:89]
	v_mfma_f32_16x16x32_bf16 v[90:93], v[242:245], v[216:219], v[90:93]
	v_mfma_f32_16x16x32_bf16 v[94:97], v[242:245], v[220:223], v[94:97]
	v_mfma_f32_16x16x32_bf16 v[98:101], v[242:245], v[234:237], v[98:101]
	ds_read_b128 v[242:245], v233 offset:2048
	s_waitcnt lgkmcnt(6)
	v_mfma_f32_16x16x32_bf16 v[102:105], v[246:249], v[212:215], v[102:105]
	v_mfma_f32_16x16x32_bf16 v[106:109], v[246:249], v[216:219], v[106:109]
	v_mfma_f32_16x16x32_bf16 v[110:113], v[246:249], v[220:223], v[110:113]
	v_mfma_f32_16x16x32_bf16 v[114:117], v[246:249], v[234:237], v[114:117]
	ds_read_b128 v[246:249], v233 offset:4096
	s_waitcnt lgkmcnt(5)
	v_mfma_f32_16x16x32_bf16 v[118:121], v[250:253], v[212:215], v[118:121]
	v_mfma_f32_16x16x32_bf16 v[122:125], v[250:253], v[216:219], v[122:125]
	v_mfma_f32_16x16x32_bf16 v[126:129], v[250:253], v[220:223], v[126:129]
	v_mfma_f32_16x16x32_bf16 v[2:5], v[250:253], v[234:237], v[2:5]
	ds_read_b128 v[250:253], v233 offset:6144
	s_waitcnt lgkmcnt(3)
	v_mfma_f32_16x16x32_bf16 v[6:9], v[238:241], v[130:133], v[6:9]
	v_mfma_f32_16x16x32_bf16 v[10:13], v[238:241], v[134:137], v[10:13]
	v_mfma_f32_16x16x32_bf16 v[14:17], v[238:241], v[138:141], v[14:17]
	v_mfma_f32_16x16x32_bf16 v[18:21], v[238:241], v[142:145], v[18:21]
	ds_read_b128 v[238:241], v233 offset:8192
	s_waitcnt lgkmcnt(3)
	v_mfma_f32_16x16x32_bf16 v[22:25], v[242:245], v[130:133], v[22:25]
	v_mfma_f32_16x16x32_bf16 v[26:29], v[242:245], v[134:137], v[26:29]
	v_mfma_f32_16x16x32_bf16 v[30:33], v[242:245], v[138:141], v[30:33]
	v_mfma_f32_16x16x32_bf16 v[34:37], v[242:245], v[142:145], v[34:37]
	ds_read_b128 v[242:245], v233 offset:10240
	s_waitcnt lgkmcnt(3)
	v_mfma_f32_16x16x32_bf16 v[38:41], v[246:249], v[130:133], v[38:41]
	v_mfma_f32_16x16x32_bf16 v[42:45], v[246:249], v[134:137], v[42:45]
	v_mfma_f32_16x16x32_bf16 v[46:49], v[246:249], v[138:141], v[46:49]
	v_mfma_f32_16x16x32_bf16 v[50:53], v[246:249], v[142:145], v[50:53]
	ds_read_b128 v[246:249], v233 offset:12288
	s_waitcnt lgkmcnt(3)
	v_mfma_f32_16x16x32_bf16 v[54:57], v[250:253], v[130:133], v[54:57]
	v_mfma_f32_16x16x32_bf16 v[58:61], v[250:253], v[134:137], v[58:61]
	v_mfma_f32_16x16x32_bf16 v[62:65], v[250:253], v[138:141], v[62:65]
	v_mfma_f32_16x16x32_bf16 v[66:69], v[250:253], v[142:145], v[66:69]
	ds_read_b128 v[250:253], v233 offset:14336
	s_waitcnt lgkmcnt(3)
	v_mfma_f32_16x16x32_bf16 v[70:73], v[238:241], v[130:133], v[70:73]
	v_mfma_f32_16x16x32_bf16 v[74:77], v[238:241], v[134:137], v[74:77]
	v_mfma_f32_16x16x32_bf16 v[78:81], v[238:241], v[138:141], v[78:81]
	v_mfma_f32_16x16x32_bf16 v[82:85], v[238:241], v[142:145], v[82:85]
	s_waitcnt lgkmcnt(2)
	v_mfma_f32_16x16x32_bf16 v[86:89], v[242:245], v[130:133], v[86:89]
	v_mfma_f32_16x16x32_bf16 v[90:93], v[242:245], v[134:137], v[90:93]
	v_mfma_f32_16x16x32_bf16 v[94:97], v[242:245], v[138:141], v[94:97]
	v_mfma_f32_16x16x32_bf16 v[98:101], v[242:245], v[142:145], v[98:101]
	s_waitcnt lgkmcnt(0)
	s_waitcnt vmcnt(0)
	s_barrier
	v_mfma_f32_16x16x32_bf16 v[102:105], v[246:249], v[130:133], v[102:105]
	v_mfma_f32_16x16x32_bf16 v[106:109], v[246:249], v[134:137], v[106:109]
	v_mfma_f32_16x16x32_bf16 v[110:113], v[246:249], v[138:141], v[110:113]
	v_mfma_f32_16x16x32_bf16 v[114:117], v[246:249], v[142:145], v[114:117]
	v_mfma_f32_16x16x32_bf16 v[118:121], v[250:253], v[130:133], v[118:121]
	v_mfma_f32_16x16x32_bf16 v[122:125], v[250:253], v[134:137], v[122:125]
	v_mfma_f32_16x16x32_bf16 v[126:129], v[250:253], v[138:141], v[126:129]
	v_mfma_f32_16x16x32_bf16 v[2:5], v[250:253], v[142:145], v[2:5]
	s_nop 0
	v_readfirstlane_b32 s40, v195
	s_lshr_b32 s40, s40, 6
	s_and_b32 s41, s40, 3
	s_lshr_b32 s42, s40, 2
	s_lshr_b32 s43, s46, 6
	s_add_i32 s43, s43, s41
	s_cmp_ge_u32 s66, 0x8000
	s_cselect_b32 s67, 1, 0
	s_mov_b32 s44, 0xffff
	s_mov_b32 s45, 0
	s_bitcmp1_b64 s[44:45], s43
	s_cbranch_scc1 .Lfe_kind0
	s_mov_b32 s44, 0xc00000
	s_mov_b32 s45, 0xc0f
	s_bitcmp1_b64 s[44:45], s43
	s_cbranch_scc1 .Lfe_kind1
	s_cmp_ge_u32 s43, 44
	s_cbranch_scc1 .Lfe_kind2
	s_branch .Lfe_kind0
